# P0 weight transposes: once-read f32 weight loads non-temporal as well
# baseline (speedup 1.0000x reference)
; __device__ __forceinline__ void p0_transpose_item(const float* W, int K, int N, bf16* WT, float* scr, int item, int lane, int nscale, float sc, int perm) {
;     const int nblk = N / 32, kb = item / nblk, nb = item % nblk, k0 = 64 * kb, n0 = 32 * nb;
;     int nd0 = n0;
;     if (perm == 1) nd0 = (n0 < 2048 ? n0 : (n0 < 3072 ? n0 + 1024 : n0 - 1024));
;     if (perm == 2) nd0 = (n0 < 1024 ? n0 : (n0 < 1536 ? n0 + 1792 : (n0 < 2688 ? n0 - 512 : n0 - 512)));
;     const float f = (n0 < nscale) ? sc : 1.f;
; #pragma unroll 8
;     for (int i = 0; i < 32; ++i) { const int kk = 2 * i + (lane >> 5); scr[kk * 33 + (lane & 31)] = W[(size_t)(k0 + kk) * N + n0 + (lane & 31)] * f; }
;     __builtin_amdgcn_wave_barrier();
.LBB0_35:
	s_lshl_b32 s18, s2, 1
	s_lshl_b32 s19, s11, 1
	v_add_u32_e32 v60, s18, v36
	v_add_u32_e32 v62, s19, v33
	v_add_u32_e32 v64, s18, v38
	v_add_u32_e32 v66, s19, v37
	v_add_u32_e32 v68, s18, v40
	v_add_u32_e32 v70, s19, v39
	v_add_u32_e32 v72, s18, v42
	v_add_u32_e32 v74, s19, v41
	v_add_u32_e32 v76, s18, v44
	v_add_u32_e32 v78, s19, v43
	v_add_u32_e32 v80, s18, v46
	v_add_u32_e32 v82, s19, v45
	v_add_u32_e32 v84, s18, v48
	v_add_u32_e32 v86, s19, v47
	v_add_u32_e32 v88, s18, v50
	v_add_u32_e32 v90, s19, v49
	v_ashrrev_i32_e32 v61, 31, v60
	v_ashrrev_i32_e32 v63, 31, v62
	v_ashrrev_i32_e32 v65, 31, v64
	v_ashrrev_i32_e32 v67, 31, v66
	v_ashrrev_i32_e32 v69, 31, v68
	v_ashrrev_i32_e32 v71, 31, v70
	v_ashrrev_i32_e32 v73, 31, v72
	v_ashrrev_i32_e32 v75, 31, v74
	v_ashrrev_i32_e32 v77, 31, v76
	v_ashrrev_i32_e32 v79, 31, v78
	v_ashrrev_i32_e32 v81, 31, v80
	v_ashrrev_i32_e32 v83, 31, v82
	v_ashrrev_i32_e32 v85, 31, v84
	v_ashrrev_i32_e32 v87, 31, v86
	v_ashrrev_i32_e32 v89, 31, v88
	v_ashrrev_i32_e32 v91, 31, v90
	v_lshlrev_b64 v[60:61], 12, v[60:61]
	v_lshlrev_b64 v[62:63], 12, v[62:63]
	v_lshlrev_b64 v[64:65], 12, v[64:65]
	v_lshlrev_b64 v[66:67], 12, v[66:67]
	v_lshlrev_b64 v[68:69], 12, v[68:69]
	v_lshlrev_b64 v[70:71], 12, v[70:71]
	v_lshlrev_b64 v[72:73], 12, v[72:73]
	v_lshlrev_b64 v[74:75], 12, v[74:75]
	v_lshlrev_b64 v[76:77], 12, v[76:77]
	v_lshlrev_b64 v[78:79], 12, v[78:79]
	v_lshlrev_b64 v[80:81], 12, v[80:81]
	v_lshlrev_b64 v[82:83], 12, v[82:83]
	v_lshlrev_b64 v[84:85], 12, v[84:85]
	v_lshlrev_b64 v[86:87], 12, v[86:87]
	v_lshlrev_b64 v[88:89], 12, v[88:89]
	v_lshlrev_b64 v[90:91], 12, v[90:91]
	v_lshl_add_u64 v[60:61], v[34:35], 0, v[60:61]
	v_lshl_add_u64 v[62:63], v[34:35], 0, v[62:63]
	v_lshl_add_u64 v[64:65], v[34:35], 0, v[64:65]
	v_lshl_add_u64 v[66:67], v[34:35], 0, v[66:67]
	v_lshl_add_u64 v[68:69], v[34:35], 0, v[68:69]
	v_lshl_add_u64 v[70:71], v[34:35], 0, v[70:71]
	v_lshl_add_u64 v[72:73], v[34:35], 0, v[72:73]
	v_lshl_add_u64 v[74:75], v[34:35], 0, v[74:75]
	v_lshl_add_u64 v[76:77], v[34:35], 0, v[76:77]
	v_lshl_add_u64 v[78:79], v[34:35], 0, v[78:79]
	v_lshl_add_u64 v[80:81], v[34:35], 0, v[80:81]
	v_lshl_add_u64 v[82:83], v[34:35], 0, v[82:83]
	v_lshl_add_u64 v[84:85], v[34:35], 0, v[84:85]
	v_lshl_add_u64 v[86:87], v[34:35], 0, v[86:87]
	v_lshl_add_u64 v[88:89], v[34:35], 0, v[88:89]
	v_lshl_add_u64 v[90:91], v[34:35], 0, v[90:91]
	global_load_dword v51, v[60:61], off nt
	global_load_dword v52, v[62:63], off nt
	global_load_dword v59, v[64:65], off nt
	global_load_dword v92, v[66:67], off nt
	global_load_dword v93, v[68:69], off nt
	global_load_dword v94, v[70:71], off nt
	global_load_dword v95, v[72:73], off nt
	global_load_dword v96, v[74:75], off nt
	global_load_dword v97, v[76:77], off nt
	global_load_dword v98, v[78:79], off nt
	global_load_dword v99, v[80:81], off nt
	global_load_dword v100, v[82:83], off nt
	global_load_dword v101, v[84:85], off nt
	global_load_dword v102, v[86:87], off nt
	global_load_dword v103, v[88:89], off nt
	global_load_dword v104, v[90:91], off nt
	s_add_i32 s2, s2, 16
	s_add_i32 s11, s11, 16
	s_add_i32 s13, s13, -16
	v_add_u32_e32 v60, s18, v0
	v_add_u32_e32 v62, s19, v1
	v_add_u32_e32 v64, s18, v20
	v_add_u32_e32 v66, s19, v5
	v_add_u32_e32 v68, s18, v22
	v_add_u32_e32 v70, s19, v21
	v_add_u32_e32 v72, s18, v24
	v_add_u32_e32 v74, s19, v23
	v_add_u32_e32 v76, s18, v26
	v_add_u32_e32 v78, s19, v25
	v_add_u32_e32 v80, s18, v28
	v_add_u32_e32 v82, s19, v27
	v_add_u32_e32 v84, s18, v30
	v_add_u32_e32 v86, s19, v29
	v_add_u32_e32 v88, s18, v32
	v_add_u32_e32 v90, s19, v31
	s_cmp_lg_u32 s13, 0
	v_mad_u64_u32 v[60:61], s[18:19], v60, s14, v[4:5]
	v_mad_u64_u32 v[62:63], s[18:19], v62, s14, v[4:5]
	v_mad_u64_u32 v[64:65], s[18:19], v64, s14, v[4:5]
	v_mad_u64_u32 v[66:67], s[18:19], v66, s14, v[4:5]
	v_mad_u64_u32 v[68:69], s[18:19], v68, s14, v[4:5]
	v_mad_u64_u32 v[70:71], s[18:19], v70, s14, v[4:5]
	v_mad_u64_u32 v[72:73], s[18:19], v72, s14, v[4:5]
	v_mad_u64_u32 v[74:75], s[18:19], v74, s14, v[4:5]
	v_mad_u64_u32 v[76:77], s[18:19], v76, s14, v[4:5]
	v_mad_u64_u32 v[78:79], s[18:19], v78, s14, v[4:5]
	v_mad_u64_u32 v[80:81], s[18:19], v80, s14, v[4:5]
	v_mad_u64_u32 v[82:83], s[18:19], v82, s14, v[4:5]
	v_mad_u64_u32 v[84:85], s[18:19], v84, s14, v[4:5]
	v_mad_u64_u32 v[86:87], s[18:19], v86, s14, v[4:5]
	v_mad_u64_u32 v[88:89], s[18:19], v88, s14, v[4:5]
	v_mad_u64_u32 v[90:91], s[18:19], v90, s14, v[4:5]
	s_waitcnt vmcnt(15)
	ds_write_b32 v60, v51
	s_waitcnt vmcnt(14)
	ds_write_b32 v62, v52
	s_waitcnt vmcnt(13)
	ds_write_b32 v64, v59
	s_waitcnt vmcnt(12)
	ds_write_b32 v66, v92
	s_waitcnt vmcnt(11)
	ds_write_b32 v68, v93
	s_waitcnt vmcnt(10)
	ds_write_b32 v70, v94
	s_waitcnt vmcnt(9)
	ds_write_b32 v72, v95
	s_waitcnt vmcnt(8)
	ds_write_b32 v74, v96
	s_waitcnt vmcnt(7)
	ds_write_b32 v76, v97
	s_waitcnt vmcnt(6)
	ds_write_b32 v78, v98
	s_waitcnt vmcnt(5)
	ds_write_b32 v80, v99
	s_waitcnt vmcnt(4)
	ds_write_b32 v82, v100
	s_waitcnt vmcnt(3)
	ds_write_b32 v84, v101
	s_waitcnt vmcnt(2)
	ds_write_b32 v86, v102
	s_waitcnt vmcnt(1)
	ds_write_b32 v88, v103
	s_waitcnt vmcnt(0)
	ds_write_b32 v90, v104
	s_cbranch_scc1 .LBB0_35
; __device__ __forceinline__ unsigned cvtpk(float lo, float hi) { f32x2_t v = {lo, hi}; bf16x2_t b = __builtin_convertvector(v, bf16x2_t); return __builtin_bit_cast(unsigned, b); }
; __device__ __forceinline__ void p0_transpose_item(const float* W, int K, int N, bf16* WT, float* scr, int item, int lane, int nscale, float sc, int perm) {
;     ...
;     const int c = lane & 7;
; #pragma unroll
;     for (int j = 0; j < 4; ++j) { const int n = (lane >> 3) + 8 * j; const float* s = scr + (8 * c) * 33 + n;
;         u32x4 o; o.x = cvtpk(s[0 * 33], s[1 * 33]); o.y = cvtpk(s[2 * 33], s[3 * 33]); o.z = cvtpk(s[4 * 33], s[5 * 33]); o.w = cvtpk(s[6 * 33], s[7 * 33]);
;         *(u32x4*)(WT + (size_t)(nd0 + n) * K + k0 + 8 * c) = o; }
;     __builtin_amdgcn_wave_barrier();
	ds_read2_b32 v[38:39], v54 offset0:33 offset1:41
	ds_read2_b32 v[40:41], v54 offset1:8
	ds_read2_b32 v[42:43], v54 offset0:66 offset1:74
	ds_read2_b32 v[44:45], v54 offset0:99 offset1:107
	ds_read2_b32 v[46:47], v54 offset0:132 offset1:140
	ds_read2_b32 v[48:49], v54 offset0:165 offset1:173
	ds_read2_b32 v[50:51], v54 offset0:198 offset1:206
	ds_read2_b32 v[60:61], v54 offset0:231 offset1:239
	v_add_u32_e32 v64, s10, v53
	s_lshl_b32 s2, s12, 1
	v_ashrrev_i32_e32 v65, 31, v64
	v_lshl_add_u64 v[62:63], v[6:7], 0, s[2:3]
	v_lshlrev_b64 v[64:65], 11, v[64:65]
	s_waitcnt lgkmcnt(6)
	v_cvt_pk_bf16_f32 v34, v40, v38
	s_waitcnt lgkmcnt(4)
	v_cvt_pk_bf16_f32 v35, v42, v44
	s_waitcnt lgkmcnt(2)
	v_cvt_pk_bf16_f32 v36, v46, v48
	s_waitcnt lgkmcnt(0)
	v_cvt_pk_bf16_f32 v37, v50, v60
	v_lshl_add_u64 v[64:65], v[62:63], 0, v[64:65]
	v_add_u32_e32 v38, s10, v55
	global_store_dwordx4 v[64:65], v[34:37], off
	s_nop 1
	v_cvt_pk_bf16_f32 v34, v41, v39
	v_ashrrev_i32_e32 v39, 31, v38
	v_cvt_pk_bf16_f32 v35, v43, v45
	v_cvt_pk_bf16_f32 v36, v47, v49
	v_cvt_pk_bf16_f32 v37, v51, v61
	v_lshlrev_b64 v[38:39], 11, v[38:39]
	ds_read2_b32 v[40:41], v54 offset0:49 offset1:57
	ds_read2_b32 v[42:43], v54 offset0:16 offset1:24
	ds_read2_b32 v[44:45], v54 offset0:82 offset1:90
	ds_read2_b32 v[46:47], v54 offset0:115 offset1:123
	ds_read2_b32 v[48:49], v54 offset0:148 offset1:156
	ds_read2_b32 v[50:51], v54 offset0:181 offset1:189
	ds_read2_b32 v[60:61], v54 offset0:214 offset1:222
	ds_read2_b32 v[64:65], v54 offset0:247 offset1:255
	v_lshl_add_u64 v[38:39], v[62:63], 0, v[38:39]
	global_store_dwordx4 v[38:39], v[34:37], off
	v_add_u32_e32 v38, s10, v56
	v_ashrrev_i32_e32 v39, 31, v38
	v_lshlrev_b64 v[38:39], 11, v[38:39]
	s_waitcnt lgkmcnt(6)
	v_cvt_pk_bf16_f32 v34, v42, v40
	s_waitcnt lgkmcnt(4)
	v_cvt_pk_bf16_f32 v35, v44, v46
	s_waitcnt lgkmcnt(2)
	v_cvt_pk_bf16_f32 v36, v48, v50
	s_waitcnt lgkmcnt(0)
	v_cvt_pk_bf16_f32 v37, v60, v64
	v_lshl_add_u64 v[38:39], v[62:63], 0, v[38:39]
	global_store_dwordx4 v[38:39], v[34:37], off
	v_add_u32_e32 v38, s10, v57
	v_ashrrev_i32_e32 v39, 31, v38
	v_lshlrev_b64 v[38:39], 11, v[38:39]
	v_cvt_pk_bf16_f32 v34, v43, v41
	v_cvt_pk_bf16_f32 v35, v45, v47
	v_cvt_pk_bf16_f32 v36, v49, v51
	v_cvt_pk_bf16_f32 v37, v61, v65
	v_lshl_add_u64 v[38:39], v[62:63], 0, v[38:39]
	global_store_dwordx4 v[38:39], v[34:37], off
	s_mov_b64 s[10:11], 0

; __device__ __forceinline__ void p0_transpose_item(const float* W, int K, int N, bf16* WT, float* scr, int item, int lane, int nscale, float sc, int perm) {
;     const int nblk = N / 32, kb = item / nblk, nb = item % nblk, k0 = 64 * kb, n0 = 32 * nb;
;     int nd0 = n0;
;     if (perm == 1) nd0 = (n0 < 2048 ? n0 : (n0 < 3072 ? n0 + 1024 : n0 - 1024));
;     if (perm == 2) nd0 = (n0 < 1024 ? n0 : (n0 < 1536 ? n0 + 1792 : (n0 < 2688 ? n0 - 512 : n0 - 512)));
;     const float f = (n0 < nscale) ? sc : 1.f;
; #pragma unroll 8
;     for (int i = 0; i < 32; ++i) { const int kk = 2 * i + (lane >> 5); scr[kk * 33 + (lane & 31)] = W[(size_t)(k0 + kk) * N + n0 + (lane & 31)] * f; }
;     __builtin_amdgcn_wave_barrier();
.LBB0_39:
	s_lshl_b32 s19, s18, 1
	s_lshl_b32 s20, s13, 1
	v_add_u32_e32 v60, s19, v38
	v_add_u32_e32 v62, s20, v33
	v_add_u32_e32 v64, s19, v40
	v_add_u32_e32 v66, s20, v39
	v_add_u32_e32 v68, s19, v42
	v_add_u32_e32 v70, s20, v41
	v_add_u32_e32 v72, s19, v44
	v_add_u32_e32 v74, s20, v43
	v_add_u32_e32 v76, s19, v46
	v_add_u32_e32 v78, s20, v45
	v_add_u32_e32 v80, s19, v48
	v_add_u32_e32 v82, s20, v47
	v_add_u32_e32 v84, s19, v50
	v_add_u32_e32 v86, s20, v49
	v_add_u32_e32 v88, s19, v52
	v_add_u32_e32 v90, s20, v51
	v_ashrrev_i32_e32 v61, 31, v60
	v_ashrrev_i32_e32 v63, 31, v62
	v_ashrrev_i32_e32 v65, 31, v64
	v_ashrrev_i32_e32 v67, 31, v66
	v_ashrrev_i32_e32 v69, 31, v68
	v_ashrrev_i32_e32 v71, 31, v70
	v_ashrrev_i32_e32 v73, 31, v72
	v_ashrrev_i32_e32 v75, 31, v74
	v_ashrrev_i32_e32 v77, 31, v76
	v_ashrrev_i32_e32 v79, 31, v78
	v_ashrrev_i32_e32 v81, 31, v80
	v_ashrrev_i32_e32 v83, 31, v82
	v_ashrrev_i32_e32 v85, 31, v84
	v_ashrrev_i32_e32 v87, 31, v86
	v_ashrrev_i32_e32 v89, 31, v88
	v_ashrrev_i32_e32 v91, 31, v90
	v_lshlrev_b64 v[62:63], 14, v[62:63]
	v_lshlrev_b64 v[60:61], 14, v[60:61]
	v_lshlrev_b64 v[66:67], 14, v[66:67]
	v_lshlrev_b64 v[64:65], 14, v[64:65]
	v_lshlrev_b64 v[70:71], 14, v[70:71]
	v_lshlrev_b64 v[68:69], 14, v[68:69]
	v_lshlrev_b64 v[74:75], 14, v[74:75]
	v_lshlrev_b64 v[72:73], 14, v[72:73]
	v_lshlrev_b64 v[78:79], 14, v[78:79]
	v_lshlrev_b64 v[76:77], 14, v[76:77]
	v_lshlrev_b64 v[82:83], 14, v[82:83]
	v_lshlrev_b64 v[80:81], 14, v[80:81]
	v_lshlrev_b64 v[86:87], 14, v[86:87]
	v_lshlrev_b64 v[84:85], 14, v[84:85]
	v_lshlrev_b64 v[90:91], 14, v[90:91]
	v_lshlrev_b64 v[88:89], 14, v[88:89]
	v_lshl_add_u64 v[60:61], v[34:35], 0, v[60:61]
	v_lshl_add_u64 v[62:63], v[34:35], 0, v[62:63]
	v_lshl_add_u64 v[64:65], v[34:35], 0, v[64:65]
	v_lshl_add_u64 v[66:67], v[34:35], 0, v[66:67]
	v_lshl_add_u64 v[68:69], v[34:35], 0, v[68:69]
	v_lshl_add_u64 v[70:71], v[34:35], 0, v[70:71]
	v_lshl_add_u64 v[72:73], v[34:35], 0, v[72:73]
	v_lshl_add_u64 v[74:75], v[34:35], 0, v[74:75]
	v_lshl_add_u64 v[76:77], v[34:35], 0, v[76:77]
	v_lshl_add_u64 v[78:79], v[34:35], 0, v[78:79]
	v_lshl_add_u64 v[80:81], v[34:35], 0, v[80:81]
	v_lshl_add_u64 v[82:83], v[34:35], 0, v[82:83]
	v_lshl_add_u64 v[84:85], v[34:35], 0, v[84:85]
	v_lshl_add_u64 v[86:87], v[34:35], 0, v[86:87]
	v_lshl_add_u64 v[88:89], v[34:35], 0, v[88:89]
	v_lshl_add_u64 v[90:91], v[34:35], 0, v[90:91]
	global_load_dword v60, v[60:61], off nt
	s_nop 0
	global_load_dword v61, v[62:63], off nt
	s_nop 0
	global_load_dword v62, v[64:65], off nt
	global_load_dword v63, v[66:67], off nt
	s_nop 0
	global_load_dword v64, v[68:69], off nt
	global_load_dword v65, v[70:71], off nt
	global_load_dword v66, v[72:73], off nt
	global_load_dword v67, v[74:75], off nt
	s_nop 0
	global_load_dword v68, v[76:77], off nt
	global_load_dword v69, v[78:79], off nt
	global_load_dword v70, v[80:81], off nt
	global_load_dword v71, v[82:83], off nt
	global_load_dword v72, v[84:85], off nt
	global_load_dword v73, v[86:87], off nt
	global_load_dword v74, v[88:89], off nt
	global_load_dword v75, v[90:91], off nt
	s_add_i32 s18, s18, 16
	s_add_i32 s13, s13, 16
	s_add_i32 s2, s2, -16
	v_add_u32_e32 v59, s19, v0
	v_add_u32_e32 v78, s20, v1
	v_add_u32_e32 v80, s19, v20
	v_add_u32_e32 v82, s20, v5
	v_add_u32_e32 v84, s19, v22
	v_add_u32_e32 v86, s20, v21
	v_add_u32_e32 v88, s19, v24
	v_add_u32_e32 v90, s20, v23
	v_add_u32_e32 v92, s19, v26
	v_add_u32_e32 v94, s20, v25
	v_add_u32_e32 v96, s19, v28
	v_add_u32_e32 v98, s20, v27
	v_add_u32_e32 v100, s19, v30
	v_add_u32_e32 v102, s20, v29
	v_add_u32_e32 v104, s19, v32
	v_add_u32_e32 v106, s20, v31
	s_cmp_lg_u32 s2, 0
	v_mad_u64_u32 v[76:77], s[20:21], v59, s14, v[4:5]
	v_mad_u64_u32 v[78:79], s[20:21], v78, s14, v[4:5]
	v_mad_u64_u32 v[80:81], s[20:21], v80, s14, v[4:5]
	v_mad_u64_u32 v[82:83], s[20:21], v82, s14, v[4:5]
	v_mad_u64_u32 v[84:85], s[20:21], v84, s14, v[4:5]
	v_mad_u64_u32 v[86:87], s[20:21], v86, s14, v[4:5]
	v_mad_u64_u32 v[88:89], s[20:21], v88, s14, v[4:5]
	v_mad_u64_u32 v[90:91], s[20:21], v90, s14, v[4:5]
	v_mad_u64_u32 v[92:93], s[20:21], v92, s14, v[4:5]
	v_mad_u64_u32 v[94:95], s[20:21], v94, s14, v[4:5]
	v_mad_u64_u32 v[96:97], s[20:21], v96, s14, v[4:5]
	v_mad_u64_u32 v[98:99], s[20:21], v98, s14, v[4:5]
	v_mad_u64_u32 v[100:101], s[20:21], v100, s14, v[4:5]
	v_mad_u64_u32 v[102:103], s[20:21], v102, s14, v[4:5]
	v_mad_u64_u32 v[104:105], s[20:21], v104, s14, v[4:5]
	v_mad_u64_u32 v[106:107], s[20:21], v106, s14, v[4:5]
	s_waitcnt vmcnt(14)
	v_pk_mul_f32 v[60:61], v[36:37], v[60:61]
	s_waitcnt vmcnt(12)
	v_pk_mul_f32 v[62:63], v[36:37], v[62:63]
	s_waitcnt vmcnt(10)
	v_pk_mul_f32 v[64:65], v[36:37], v[64:65]
	s_waitcnt vmcnt(8)
	v_pk_mul_f32 v[66:67], v[36:37], v[66:67]
	s_waitcnt vmcnt(6)
	v_pk_mul_f32 v[68:69], v[36:37], v[68:69]
	s_waitcnt vmcnt(4)
	v_pk_mul_f32 v[70:71], v[36:37], v[70:71]
	s_waitcnt vmcnt(2)
	v_pk_mul_f32 v[72:73], v[36:37], v[72:73]
	s_waitcnt vmcnt(0)
	v_pk_mul_f32 v[74:75], v[36:37], v[74:75]
	ds_write_b32 v76, v60
	ds_write_b32 v78, v61
	ds_write_b32 v80, v62
	ds_write_b32 v82, v63
	ds_write_b32 v84, v64
	ds_write_b32 v86, v65
	ds_write_b32 v88, v66
	ds_write_b32 v90, v67
	ds_write_b32 v92, v68
	ds_write_b32 v94, v69
	ds_write_b32 v96, v70
	ds_write_b32 v98, v71
	ds_write_b32 v100, v72
	ds_write_b32 v102, v73
	ds_write_b32 v104, v74
	ds_write_b32 v106, v75
	s_cbranch_scc1 .LBB0_39
; __device__ __forceinline__ unsigned cvtpk(float lo, float hi) { f32x2_t v = {lo, hi}; bf16x2_t b = __builtin_convertvector(v, bf16x2_t); return __builtin_bit_cast(unsigned, b); }
; __device__ __forceinline__ void p0_transpose_item(const float* W, int K, int N, bf16* WT, float* scr, int item, int lane, int nscale, float sc, int perm) {
;     ...
;     if (perm == 1) nd0 = (n0 < 2048 ? n0 : (n0 < 3072 ? n0 + 1024 : n0 - 1024));
;     if (perm == 2) nd0 = (n0 < 1024 ? n0 : (n0 < 1536 ? n0 + 1792 : (n0 < 2688 ? n0 - 512 : n0 - 512)));
;     const float f = (n0 < nscale) ? sc : 1.f;
; #pragma unroll 8
;     for (int i = 0; i < 32; ++i) { const int kk = 2 * i + (lane >> 5); scr[kk * 33 + (lane & 31)] = W[(size_t)(k0 + kk) * N + n0 + (lane & 31)] * f; }
;     __builtin_amdgcn_wave_barrier();
;     const int c = lane & 7;
; #pragma unroll
;     for (int j = 0; j < 4; ++j) { const int n = (lane >> 3) + 8 * j; const float* s = scr + (8 * c) * 33 + n;
;         u32x4 o; o.x = cvtpk(s[0 * 33], s[1 * 33]); o.y = cvtpk(s[2 * 33], s[3 * 33]); o.z = cvtpk(s[4 * 33], s[5 * 33]); o.w = cvtpk(s[6 * 33], s[7 * 33]);
;         *(u32x4*)(WT + (size_t)(nd0 + n) * K + k0 + 8 * c) = o; }
	s_cmpk_lt_u32 s11, 0x60
	s_cselect_b32 s2, s15, 0xfffffc00
	s_cmp_gt_u32 s11, 63
	s_cselect_b32 s2, s2, 0
	ds_read2_b32 v[38:39], v54 offset0:33 offset1:41
	ds_read2_b32 v[40:41], v54 offset1:8
	ds_read2_b32 v[42:43], v54 offset0:66 offset1:74
	ds_read2_b32 v[44:45], v54 offset0:99 offset1:107
	ds_read2_b32 v[46:47], v54 offset0:132 offset1:140
	ds_read2_b32 v[48:49], v54 offset0:165 offset1:173
	ds_read2_b32 v[50:51], v54 offset0:198 offset1:206
	ds_read2_b32 v[60:61], v54 offset0:231 offset1:239
	s_add_i32 s11, s2, s12
	v_add_u32_e32 v64, s11, v53
	s_lshl_b32 s2, s10, 1
	v_ashrrev_i32_e32 v65, 31, v64
	v_lshl_add_u64 v[62:63], v[10:11], 0, s[2:3]
	v_lshlrev_b64 v[64:65], 11, v[64:65]
	s_waitcnt lgkmcnt(6)
	v_cvt_pk_bf16_f32 v34, v40, v38
	s_waitcnt lgkmcnt(4)
	v_cvt_pk_bf16_f32 v35, v42, v44
	s_waitcnt lgkmcnt(2)
	v_cvt_pk_bf16_f32 v36, v46, v48
	s_waitcnt lgkmcnt(0)
	v_cvt_pk_bf16_f32 v37, v50, v60
	v_lshl_add_u64 v[64:65], v[62:63], 0, v[64:65]
	v_add_u32_e32 v38, s11, v55
	global_store_dwordx4 v[64:65], v[34:37], off
	s_nop 1
	v_cvt_pk_bf16_f32 v34, v41, v39
	v_ashrrev_i32_e32 v39, 31, v38
	v_cvt_pk_bf16_f32 v35, v43, v45
	v_cvt_pk_bf16_f32 v36, v47, v49
	v_cvt_pk_bf16_f32 v37, v51, v61
	v_lshlrev_b64 v[38:39], 11, v[38:39]
	ds_read2_b32 v[40:41], v54 offset0:49 offset1:57
	ds_read2_b32 v[42:43], v54 offset0:16 offset1:24
	ds_read2_b32 v[44:45], v54 offset0:82 offset1:90
	ds_read2_b32 v[46:47], v54 offset0:115 offset1:123
	ds_read2_b32 v[48:49], v54 offset0:148 offset1:156
	ds_read2_b32 v[50:51], v54 offset0:181 offset1:189
	ds_read2_b32 v[60:61], v54 offset0:214 offset1:222
	ds_read2_b32 v[64:65], v54 offset0:247 offset1:255
	v_lshl_add_u64 v[38:39], v[62:63], 0, v[38:39]
	global_store_dwordx4 v[38:39], v[34:37], off
	v_add_u32_e32 v38, s11, v56
	v_ashrrev_i32_e32 v39, 31, v38
	v_lshlrev_b64 v[38:39], 11, v[38:39]
	s_waitcnt lgkmcnt(6)
	v_cvt_pk_bf16_f32 v34, v42, v40
	s_waitcnt lgkmcnt(4)
	v_cvt_pk_bf16_f32 v35, v44, v46
	s_waitcnt lgkmcnt(2)
	v_cvt_pk_bf16_f32 v36, v48, v50
	s_waitcnt lgkmcnt(0)
	v_cvt_pk_bf16_f32 v37, v60, v64
	v_lshl_add_u64 v[38:39], v[62:63], 0, v[38:39]
	global_store_dwordx4 v[38:39], v[34:37], off
	v_add_u32_e32 v38, s11, v57
	v_ashrrev_i32_e32 v39, 31, v38
	v_lshlrev_b64 v[38:39], 11, v[38:39]
	v_cvt_pk_bf16_f32 v34, v43, v41
	v_cvt_pk_bf16_f32 v35, v45, v47
	v_cvt_pk_bf16_f32 v36, v49, v51
	v_cvt_pk_bf16_f32 v37, v61, v65
	v_lshl_add_u64 v[38:39], v[62:63], 0, v[38:39]
	global_store_dwordx4 v[38:39], v[34:37], off

; __device__ __forceinline__ void p0_transpose_item(const float* W, int K, int N, bf16* WT, float* scr, int item, int lane, int nscale, float sc, int perm) {
;     const int nblk = N / 32, kb = item / nblk, nb = item % nblk, k0 = 64 * kb, n0 = 32 * nb;
;     int nd0 = n0;
;     if (perm == 1) nd0 = (n0 < 2048 ? n0 : (n0 < 3072 ? n0 + 1024 : n0 - 1024));
;     if (perm == 2) nd0 = (n0 < 1024 ? n0 : (n0 < 1536 ? n0 + 1792 : (n0 < 2688 ? n0 - 512 : n0 - 512)));
;     const float f = (n0 < nscale) ? sc : 1.f;
; #pragma unroll 8
;     for (int i = 0; i < 32; ++i) { const int kk = 2 * i + (lane >> 5); scr[kk * 33 + (lane & 31)] = W[(size_t)(k0 + kk) * N + n0 + (lane & 31)] * f; }
;     __builtin_amdgcn_wave_barrier();
.LBB0_44:
	s_lshl_b32 s18, s2, 1
	s_lshl_b32 s19, s11, 1
	v_add_u32_e32 v60, s18, v36
	v_add_u32_e32 v62, s19, v33
	v_add_u32_e32 v64, s18, v38
	v_add_u32_e32 v66, s19, v37
	v_add_u32_e32 v68, s18, v40
	v_add_u32_e32 v70, s19, v39
	v_add_u32_e32 v72, s18, v42
	v_add_u32_e32 v74, s19, v41
	v_add_u32_e32 v76, s18, v44
	v_add_u32_e32 v78, s19, v43
	v_add_u32_e32 v80, s18, v46
	v_add_u32_e32 v82, s19, v45
	v_add_u32_e32 v84, s18, v48
	v_add_u32_e32 v86, s19, v47
	v_add_u32_e32 v88, s18, v50
	v_add_u32_e32 v90, s19, v49
	v_ashrrev_i32_e32 v61, 31, v60
	v_ashrrev_i32_e32 v63, 31, v62
	v_ashrrev_i32_e32 v65, 31, v64
	v_ashrrev_i32_e32 v67, 31, v66
	v_ashrrev_i32_e32 v69, 31, v68
	v_ashrrev_i32_e32 v71, 31, v70
	v_ashrrev_i32_e32 v73, 31, v72
	v_ashrrev_i32_e32 v75, 31, v74
	v_ashrrev_i32_e32 v77, 31, v76
	v_ashrrev_i32_e32 v79, 31, v78
	v_ashrrev_i32_e32 v81, 31, v80
	v_ashrrev_i32_e32 v83, 31, v82
	v_ashrrev_i32_e32 v85, 31, v84
	v_ashrrev_i32_e32 v87, 31, v86
	v_ashrrev_i32_e32 v89, 31, v88
	v_ashrrev_i32_e32 v91, 31, v90
	v_lshlrev_b64 v[60:61], 12, v[60:61]
	v_lshlrev_b64 v[62:63], 12, v[62:63]
	v_lshlrev_b64 v[64:65], 12, v[64:65]
	v_lshlrev_b64 v[66:67], 12, v[66:67]
	v_lshlrev_b64 v[68:69], 12, v[68:69]
	v_lshlrev_b64 v[70:71], 12, v[70:71]
	v_lshlrev_b64 v[72:73], 12, v[72:73]
	v_lshlrev_b64 v[74:75], 12, v[74:75]
	v_lshlrev_b64 v[76:77], 12, v[76:77]
	v_lshlrev_b64 v[78:79], 12, v[78:79]
	v_lshlrev_b64 v[80:81], 12, v[80:81]
	v_lshlrev_b64 v[82:83], 12, v[82:83]
	v_lshlrev_b64 v[84:85], 12, v[84:85]
	v_lshlrev_b64 v[86:87], 12, v[86:87]
	v_lshlrev_b64 v[88:89], 12, v[88:89]
	v_lshlrev_b64 v[90:91], 12, v[90:91]
	v_lshl_add_u64 v[60:61], v[34:35], 0, v[60:61]
	v_lshl_add_u64 v[62:63], v[34:35], 0, v[62:63]
	v_lshl_add_u64 v[64:65], v[34:35], 0, v[64:65]
	v_lshl_add_u64 v[66:67], v[34:35], 0, v[66:67]
	v_lshl_add_u64 v[68:69], v[34:35], 0, v[68:69]
	v_lshl_add_u64 v[70:71], v[34:35], 0, v[70:71]
	v_lshl_add_u64 v[72:73], v[34:35], 0, v[72:73]
	v_lshl_add_u64 v[74:75], v[34:35], 0, v[74:75]
	v_lshl_add_u64 v[76:77], v[34:35], 0, v[76:77]
	v_lshl_add_u64 v[78:79], v[34:35], 0, v[78:79]
	v_lshl_add_u64 v[80:81], v[34:35], 0, v[80:81]
	v_lshl_add_u64 v[82:83], v[34:35], 0, v[82:83]
	v_lshl_add_u64 v[84:85], v[34:35], 0, v[84:85]
	v_lshl_add_u64 v[86:87], v[34:35], 0, v[86:87]
	v_lshl_add_u64 v[88:89], v[34:35], 0, v[88:89]
	v_lshl_add_u64 v[90:91], v[34:35], 0, v[90:91]
	global_load_dword v51, v[60:61], off nt
	global_load_dword v52, v[62:63], off nt
	global_load_dword v59, v[64:65], off nt
	global_load_dword v92, v[66:67], off nt
	global_load_dword v93, v[68:69], off nt
	global_load_dword v94, v[70:71], off nt
	global_load_dword v95, v[72:73], off nt
	global_load_dword v96, v[74:75], off nt
	global_load_dword v97, v[76:77], off nt
	global_load_dword v98, v[78:79], off nt
	global_load_dword v99, v[80:81], off nt
	global_load_dword v100, v[82:83], off nt
	global_load_dword v101, v[84:85], off nt
	global_load_dword v102, v[86:87], off nt
	global_load_dword v103, v[88:89], off nt
	global_load_dword v104, v[90:91], off nt
	s_add_i32 s2, s2, 16
	s_add_i32 s11, s11, 16
	s_add_i32 s13, s13, -16
	v_add_u32_e32 v60, s18, v0
	v_add_u32_e32 v62, s19, v1
	v_add_u32_e32 v64, s18, v20
	v_add_u32_e32 v66, s19, v5
	v_add_u32_e32 v68, s18, v22
	v_add_u32_e32 v70, s19, v21
	v_add_u32_e32 v72, s18, v24
	v_add_u32_e32 v74, s19, v23
	v_add_u32_e32 v76, s18, v26
	v_add_u32_e32 v78, s19, v25
	v_add_u32_e32 v80, s18, v28
	v_add_u32_e32 v82, s19, v27
	v_add_u32_e32 v84, s18, v30
	v_add_u32_e32 v86, s19, v29
	v_add_u32_e32 v88, s18, v32
	v_add_u32_e32 v90, s19, v31
	s_cmp_lg_u32 s13, 0
	v_mad_u64_u32 v[60:61], s[18:19], v60, s14, v[4:5]
	v_mad_u64_u32 v[62:63], s[18:19], v62, s14, v[4:5]
	v_mad_u64_u32 v[64:65], s[18:19], v64, s14, v[4:5]
	v_mad_u64_u32 v[66:67], s[18:19], v66, s14, v[4:5]
	v_mad_u64_u32 v[68:69], s[18:19], v68, s14, v[4:5]
	v_mad_u64_u32 v[70:71], s[18:19], v70, s14, v[4:5]
	v_mad_u64_u32 v[72:73], s[18:19], v72, s14, v[4:5]
	v_mad_u64_u32 v[74:75], s[18:19], v74, s14, v[4:5]
	v_mad_u64_u32 v[76:77], s[18:19], v76, s14, v[4:5]
	v_mad_u64_u32 v[78:79], s[18:19], v78, s14, v[4:5]
	v_mad_u64_u32 v[80:81], s[18:19], v80, s14, v[4:5]
	v_mad_u64_u32 v[82:83], s[18:19], v82, s14, v[4:5]
	v_mad_u64_u32 v[84:85], s[18:19], v84, s14, v[4:5]
	v_mad_u64_u32 v[86:87], s[18:19], v86, s14, v[4:5]
	v_mad_u64_u32 v[88:89], s[18:19], v88, s14, v[4:5]
	v_mad_u64_u32 v[90:91], s[18:19], v90, s14, v[4:5]
	s_waitcnt vmcnt(15)
	ds_write_b32 v60, v51
	s_waitcnt vmcnt(14)
	ds_write_b32 v62, v52
	s_waitcnt vmcnt(13)
	ds_write_b32 v64, v59
	s_waitcnt vmcnt(12)
	ds_write_b32 v66, v92
	s_waitcnt vmcnt(11)
	ds_write_b32 v68, v93
	s_waitcnt vmcnt(10)
	ds_write_b32 v70, v94
	s_waitcnt vmcnt(9)
	ds_write_b32 v72, v95
	s_waitcnt vmcnt(8)
	ds_write_b32 v74, v96
	s_waitcnt vmcnt(7)
	ds_write_b32 v76, v97
	s_waitcnt vmcnt(6)
	ds_write_b32 v78, v98
	s_waitcnt vmcnt(5)
	ds_write_b32 v80, v99
	s_waitcnt vmcnt(4)
	ds_write_b32 v82, v100
	s_waitcnt vmcnt(3)
	ds_write_b32 v84, v101
	s_waitcnt vmcnt(2)
	ds_write_b32 v86, v102
	s_waitcnt vmcnt(1)
	ds_write_b32 v88, v103
	s_waitcnt vmcnt(0)
	ds_write_b32 v90, v104
	s_cbranch_scc1 .LBB0_44
; __device__ __forceinline__ unsigned cvtpk(float lo, float hi) { f32x2_t v = {lo, hi}; bf16x2_t b = __builtin_convertvector(v, bf16x2_t); return __builtin_bit_cast(unsigned, b); }
; __device__ __forceinline__ void p0_transpose_item(const float* W, int K, int N, bf16* WT, float* scr, int item, int lane, int nscale, float sc, int perm) {
;     ...
;     const int c = lane & 7;
; #pragma unroll
;     for (int j = 0; j < 4; ++j) { const int n = (lane >> 3) + 8 * j; const float* s = scr + (8 * c) * 33 + n;
;         u32x4 o; o.x = cvtpk(s[0 * 33], s[1 * 33]); o.y = cvtpk(s[2 * 33], s[3 * 33]); o.z = cvtpk(s[4 * 33], s[5 * 33]); o.w = cvtpk(s[6 * 33], s[7 * 33]);
;         *(u32x4*)(WT + (size_t)(nd0 + n) * K + k0 + 8 * c) = o; }
	ds_read2_b32 v[38:39], v54 offset0:33 offset1:41
	ds_read2_b32 v[40:41], v54 offset1:8
	ds_read2_b32 v[42:43], v54 offset0:66 offset1:74
	ds_read2_b32 v[44:45], v54 offset0:99 offset1:107
	ds_read2_b32 v[46:47], v54 offset0:132 offset1:140
	ds_read2_b32 v[48:49], v54 offset0:165 offset1:173
	ds_read2_b32 v[50:51], v54 offset0:198 offset1:206
	ds_read2_b32 v[60:61], v54 offset0:231 offset1:239
	v_add_u32_e32 v64, s10, v53
	s_lshl_b32 s2, s12, 1
	v_ashrrev_i32_e32 v65, 31, v64
	v_lshl_add_u64 v[62:63], v[14:15], 0, s[2:3]
	v_lshlrev_b64 v[64:65], 11, v[64:65]
	s_waitcnt lgkmcnt(6)
	v_cvt_pk_bf16_f32 v34, v40, v38
	s_waitcnt lgkmcnt(4)
	v_cvt_pk_bf16_f32 v35, v42, v44
	s_waitcnt lgkmcnt(2)
	v_cvt_pk_bf16_f32 v36, v46, v48
	s_waitcnt lgkmcnt(0)
	v_cvt_pk_bf16_f32 v37, v50, v60
	v_lshl_add_u64 v[64:65], v[62:63], 0, v[64:65]
	v_add_u32_e32 v38, s10, v55
	global_store_dwordx4 v[64:65], v[34:37], off
	s_nop 1
	v_cvt_pk_bf16_f32 v34, v41, v39
	v_ashrrev_i32_e32 v39, 31, v38
	v_cvt_pk_bf16_f32 v35, v43, v45
	v_cvt_pk_bf16_f32 v36, v47, v49
	v_cvt_pk_bf16_f32 v37, v51, v61
	v_lshlrev_b64 v[38:39], 11, v[38:39]
	ds_read2_b32 v[40:41], v54 offset0:49 offset1:57
	ds_read2_b32 v[42:43], v54 offset0:16 offset1:24
	ds_read2_b32 v[44:45], v54 offset0:82 offset1:90
	ds_read2_b32 v[46:47], v54 offset0:115 offset1:123
	ds_read2_b32 v[48:49], v54 offset0:148 offset1:156
	ds_read2_b32 v[50:51], v54 offset0:181 offset1:189
	ds_read2_b32 v[60:61], v54 offset0:214 offset1:222
	ds_read2_b32 v[64:65], v54 offset0:247 offset1:255
	v_lshl_add_u64 v[38:39], v[62:63], 0, v[38:39]
	global_store_dwordx4 v[38:39], v[34:37], off
	v_add_u32_e32 v38, s10, v56
	v_ashrrev_i32_e32 v39, 31, v38
	v_lshlrev_b64 v[38:39], 11, v[38:39]
	s_waitcnt lgkmcnt(6)
	v_cvt_pk_bf16_f32 v34, v42, v40
	s_waitcnt lgkmcnt(4)
	v_cvt_pk_bf16_f32 v35, v44, v46
	s_waitcnt lgkmcnt(2)
	v_cvt_pk_bf16_f32 v36, v48, v50
	s_waitcnt lgkmcnt(0)
	v_cvt_pk_bf16_f32 v37, v60, v64
	v_lshl_add_u64 v[38:39], v[62:63], 0, v[38:39]
	global_store_dwordx4 v[38:39], v[34:37], off
	v_add_u32_e32 v38, s10, v57
	v_ashrrev_i32_e32 v39, 31, v38
	v_lshlrev_b64 v[38:39], 11, v[38:39]
	v_cvt_pk_bf16_f32 v34, v43, v41
	v_cvt_pk_bf16_f32 v35, v45, v47
	v_cvt_pk_bf16_f32 v36, v49, v51
	v_cvt_pk_bf16_f32 v37, v61, v65
	v_lshl_add_u64 v[38:39], v[62:63], 0, v[38:39]
	global_store_dwordx4 v[38:39], v[34:37], off

; __device__ __forceinline__ unsigned cvtpk(float lo, float hi) { f32x2_t v = {lo, hi}; bf16x2_t b = __builtin_convertvector(v, bf16x2_t); return __builtin_bit_cast(unsigned, b); }
; __device__ __forceinline__ void p0_transpose_item(const float* W, int K, int N, bf16* WT, float* scr, int item, int lane, int nscale, float sc, int perm) {
;     ...
; #pragma unroll 8
;     for (int i = 0; i < 32; ++i) { const int kk = 2 * i + (lane >> 5); scr[kk * 33 + (lane & 31)] = W[(size_t)(k0 + kk) * N + n0 + (lane & 31)] * f; }
;     __builtin_amdgcn_wave_barrier();
;     const int c = lane & 7;
; #pragma unroll
;     for (int j = 0; j < 4; ++j) { const int n = (lane >> 3) + 8 * j; const float* s = scr + (8 * c) * 33 + n;
;         u32x4 o; o.x = cvtpk(s[0 * 33], s[1 * 33]); o.y = cvtpk(s[2 * 33], s[3 * 33]); o.z = cvtpk(s[4 * 33], s[5 * 33]); o.w = cvtpk(s[6 * 33], s[7 * 33]);
;         *(u32x4*)(WT + (size_t)(nd0 + n) * K + k0 + 8 * c) = o; }
.LBB0_53:
	s_lshl_b32 s18, s12, 1
	s_lshl_b32 s19, s11, 1
	v_add_u32_e32 v51, s18, v36
	v_add_u32_e32 v52, s19, v33
	v_add_u32_e32 v59, s18, v38
	v_add_u32_e32 v66, s19, v37
	v_add_u32_e32 v68, s18, v40
	v_add_u32_e32 v70, s19, v39
	v_add_u32_e32 v72, s18, v42
	v_add_u32_e32 v74, s19, v41
	v_add_u32_e32 v76, s18, v44
	v_add_u32_e32 v78, s19, v43
	v_add_u32_e32 v80, s18, v46
	v_add_u32_e32 v82, s19, v45
	v_add_u32_e32 v84, s18, v48
	v_add_u32_e32 v86, s19, v47
	v_add_u32_e32 v88, s18, v50
	v_add_u32_e32 v90, s19, v49
	v_mad_i64_i32 v[60:61], s[20:21], v51, s16, v[34:35]
	v_mad_i64_i32 v[62:63], s[20:21], v52, s16, v[34:35]
	v_mad_i64_i32 v[64:65], s[20:21], v59, s16, v[34:35]
	v_mad_i64_i32 v[66:67], s[20:21], v66, s16, v[34:35]
	v_mad_i64_i32 v[68:69], s[20:21], v68, s16, v[34:35]
	v_mad_i64_i32 v[70:71], s[20:21], v70, s16, v[34:35]
	v_mad_i64_i32 v[72:73], s[20:21], v72, s16, v[34:35]
	v_mad_i64_i32 v[74:75], s[20:21], v74, s16, v[34:35]
	v_mad_i64_i32 v[76:77], s[20:21], v76, s16, v[34:35]
	v_mad_i64_i32 v[78:79], s[20:21], v78, s16, v[34:35]
	v_mad_i64_i32 v[80:81], s[20:21], v80, s16, v[34:35]
	v_mad_i64_i32 v[82:83], s[20:21], v82, s16, v[34:35]
	v_mad_i64_i32 v[84:85], s[20:21], v84, s16, v[34:35]
	v_mad_i64_i32 v[86:87], s[20:21], v86, s16, v[34:35]
	v_mad_i64_i32 v[88:89], s[20:21], v88, s16, v[34:35]
	v_mad_i64_i32 v[90:91], s[20:21], v90, s16, v[34:35]
	global_load_dword v51, v[60:61], off nt
	global_load_dword v52, v[62:63], off nt
	global_load_dword v59, v[64:65], off nt
	global_load_dword v92, v[66:67], off nt
	global_load_dword v93, v[68:69], off nt
	global_load_dword v94, v[70:71], off nt
	global_load_dword v95, v[72:73], off nt
	global_load_dword v96, v[74:75], off nt
	global_load_dword v97, v[76:77], off nt
	global_load_dword v98, v[78:79], off nt
	global_load_dword v99, v[80:81], off nt
	global_load_dword v100, v[82:83], off nt
	global_load_dword v101, v[84:85], off nt
	global_load_dword v102, v[86:87], off nt
	global_load_dword v103, v[88:89], off nt
	global_load_dword v104, v[90:91], off nt
	s_add_i32 s12, s12, 16
	s_add_i32 s11, s11, 16
	s_add_i32 s13, s13, -16
	v_add_u32_e32 v60, s18, v0
	v_add_u32_e32 v62, s19, v1
	v_add_u32_e32 v64, s18, v20
	v_add_u32_e32 v66, s19, v5
	v_add_u32_e32 v68, s18, v22
	v_add_u32_e32 v70, s19, v21
	v_add_u32_e32 v72, s18, v24
	v_add_u32_e32 v74, s19, v23
	v_add_u32_e32 v76, s18, v26
	v_add_u32_e32 v78, s19, v25
	v_add_u32_e32 v80, s18, v28
	v_add_u32_e32 v82, s19, v27
	v_add_u32_e32 v84, s18, v30
	v_add_u32_e32 v86, s19, v29
	v_add_u32_e32 v88, s18, v32
	v_add_u32_e32 v90, s19, v31
	s_cmp_lg_u32 s13, 0
	v_mad_u64_u32 v[60:61], s[18:19], v60, s14, v[4:5]
	v_mad_u64_u32 v[62:63], s[18:19], v62, s14, v[4:5]
	v_mad_u64_u32 v[64:65], s[18:19], v64, s14, v[4:5]
	v_mad_u64_u32 v[66:67], s[18:19], v66, s14, v[4:5]
	v_mad_u64_u32 v[68:69], s[18:19], v68, s14, v[4:5]
	v_mad_u64_u32 v[70:71], s[18:19], v70, s14, v[4:5]
	v_mad_u64_u32 v[72:73], s[18:19], v72, s14, v[4:5]
	v_mad_u64_u32 v[74:75], s[18:19], v74, s14, v[4:5]
	v_mad_u64_u32 v[76:77], s[18:19], v76, s14, v[4:5]
	v_mad_u64_u32 v[78:79], s[18:19], v78, s14, v[4:5]
	v_mad_u64_u32 v[80:81], s[18:19], v80, s14, v[4:5]
	v_mad_u64_u32 v[82:83], s[18:19], v82, s14, v[4:5]
	v_mad_u64_u32 v[84:85], s[18:19], v84, s14, v[4:5]
	v_mad_u64_u32 v[86:87], s[18:19], v86, s14, v[4:5]
	v_mad_u64_u32 v[88:89], s[18:19], v88, s14, v[4:5]
	v_mad_u64_u32 v[90:91], s[18:19], v90, s14, v[4:5]
	s_waitcnt vmcnt(15)
	ds_write_b32 v60, v51
	s_waitcnt vmcnt(14)
	ds_write_b32 v62, v52
	s_waitcnt vmcnt(13)
	ds_write_b32 v64, v59
	s_waitcnt vmcnt(12)
	ds_write_b32 v66, v92
	s_waitcnt vmcnt(11)
	ds_write_b32 v68, v93
	s_waitcnt vmcnt(10)
	ds_write_b32 v70, v94
	s_waitcnt vmcnt(9)
	ds_write_b32 v72, v95
	s_waitcnt vmcnt(8)
	ds_write_b32 v74, v96
	s_waitcnt vmcnt(7)
	ds_write_b32 v76, v97
	s_waitcnt vmcnt(6)
	ds_write_b32 v78, v98
	s_waitcnt vmcnt(5)
	ds_write_b32 v80, v99
	s_waitcnt vmcnt(4)
	ds_write_b32 v82, v100
	s_waitcnt vmcnt(3)
	ds_write_b32 v84, v101
	s_waitcnt vmcnt(2)
	ds_write_b32 v86, v102
	s_waitcnt vmcnt(1)
	ds_write_b32 v88, v103
	s_waitcnt vmcnt(0)
	ds_write_b32 v90, v104
	s_cbranch_scc1 .LBB0_53
	ds_read2_b32 v[38:39], v54 offset0:33 offset1:41
	ds_read2_b32 v[40:41], v54 offset1:8
	ds_read2_b32 v[42:43], v54 offset0:66 offset1:74
	ds_read2_b32 v[44:45], v54 offset0:99 offset1:107
	ds_read2_b32 v[46:47], v54 offset0:132 offset1:140
	ds_read2_b32 v[48:49], v54 offset0:165 offset1:173
	ds_read2_b32 v[50:51], v54 offset0:198 offset1:206
	ds_read2_b32 v[60:61], v54 offset0:231 offset1:239
	v_add_u32_e32 v64, s2, v53
	s_ashr_i32 s11, s10, 31
	v_ashrrev_i32_e32 v65, 31, v64
	v_lshl_add_u64 v[62:63], s[10:11], 1, v[18:19]
	v_lshlrev_b64 v[64:65], 11, v[64:65]
	s_waitcnt lgkmcnt(6)
	v_cvt_pk_bf16_f32 v34, v40, v38
	s_waitcnt lgkmcnt(4)
	v_cvt_pk_bf16_f32 v35, v42, v44
	s_waitcnt lgkmcnt(2)
	v_cvt_pk_bf16_f32 v36, v46, v48
	s_waitcnt lgkmcnt(0)
	v_cvt_pk_bf16_f32 v37, v50, v60
	v_lshl_add_u64 v[64:65], v[62:63], 0, v[64:65]
	v_add_u32_e32 v38, s2, v55
	global_store_dwordx4 v[64:65], v[34:37], off
	s_nop 1
	v_cvt_pk_bf16_f32 v34, v41, v39
	v_ashrrev_i32_e32 v39, 31, v38
	v_cvt_pk_bf16_f32 v35, v43, v45
	v_cvt_pk_bf16_f32 v36, v47, v49
	v_cvt_pk_bf16_f32 v37, v51, v61
	v_lshlrev_b64 v[38:39], 11, v[38:39]
	ds_read2_b32 v[40:41], v54 offset0:49 offset1:57
	ds_read2_b32 v[42:43], v54 offset0:16 offset1:24
	ds_read2_b32 v[44:45], v54 offset0:82 offset1:90
	ds_read2_b32 v[46:47], v54 offset0:115 offset1:123
	ds_read2_b32 v[48:49], v54 offset0:148 offset1:156
	ds_read2_b32 v[50:51], v54 offset0:181 offset1:189
	ds_read2_b32 v[60:61], v54 offset0:214 offset1:222
	ds_read2_b32 v[64:65], v54 offset0:247 offset1:255
	v_lshl_add_u64 v[38:39], v[62:63], 0, v[38:39]
	global_store_dwordx4 v[38:39], v[34:37], off
	v_add_u32_e32 v38, s2, v56
	v_ashrrev_i32_e32 v39, 31, v38
	v_lshlrev_b64 v[38:39], 11, v[38:39]
	s_waitcnt lgkmcnt(6)
	v_cvt_pk_bf16_f32 v34, v42, v40
	s_waitcnt lgkmcnt(4)
	v_cvt_pk_bf16_f32 v35, v44, v46
	s_waitcnt lgkmcnt(2)
	v_cvt_pk_bf16_f32 v36, v48, v50
	s_waitcnt lgkmcnt(0)
	v_cvt_pk_bf16_f32 v37, v60, v64
	v_lshl_add_u64 v[38:39], v[62:63], 0, v[38:39]
	global_store_dwordx4 v[38:39], v[34:37], off
	v_add_u32_e32 v38, s2, v57
	v_ashrrev_i32_e32 v39, 31, v38
	v_lshlrev_b64 v[38:39], 11, v[38:39]
	v_cvt_pk_bf16_f32 v34, v43, v41
	v_cvt_pk_bf16_f32 v35, v45, v47
	v_cvt_pk_bf16_f32 v36, v49, v51
	v_cvt_pk_bf16_f32 v37, v61, v65
	v_lshl_add_u64 v[38:39], v[62:63], 0, v[38:39]
	global_store_dwordx4 v[38:39], v[34:37], off
	s_branch .LBB0_29
